# GEMM phases: no per-phase setprio flips, one static s_setprio 1 for waves 4-7 before the K-loop (reset after the phase)
# baseline (speedup 1.0000x reference)
; #define PG8_STAGE(bufoff, gbase, voff) do { _Pragma("unroll") for (int _i = 0; _i < 2; ++_i) \
;         __builtin_amdgcn_global_load_lds((const unsigned*)((const char*)(gbase) + (voff)[_i]), (LAS unsigned*)(lds + (bufoff) + ldsw + _i * 8192), 16, 0, 0); } while (0)
; #define PG8_BAR __builtin_amdgcn_s_barrier()
; __device__ __forceinline__ void gemm_phase(LAS unsigned char* lds, const Params& p, const bf16_t* gA, const bf16_t* gBt, const int gM, const int gN, const int gK, const int epi, const int perm, bf16_t* const Hp, const int goff, const float coef) {
;     ...
;     for (int i = 0; i < 2; ++i) { int R, C; stage_rc(tid * 16 + i * 8192, R, C); const int Rb = perm ? ((R & ~31) + perm32(R & 31)) : R;
;         voffA[i] = (unsigned)(R * K + C) * 2u; voffB[i] = (unsigned)(Rb * K + C) * 2u; }
;     ...
;     const char* cA = (const char*)gA + (size_t)cur.pm * tstep + (cur.ks > 0 ? cur.ks * ksl : 0); const char* cB = (const char*)gBt + (size_t)cur.pn * tstep + (cur.ks > 0 ? cur.ks * ksl : 0);
;     PG8_STAGE(PG8_SB(0, 0), cB, voffB); PG8_STAGE(PG8_SB(0, 1), cB + hstep, voffB); PG8_STAGE(PG8_SA(0, 0), cA, voffA); PG8_STAGE(PG8_SA(0, 1), cA + hstep, voffA);
;     if (wr == 1) PG8_BAR;
.LBB0_159:
	v_lshrrev_b32_e32 v2, 1, v140
	v_lshrrev_b32_e32 v3, 5, v140
	v_and_b32_e32 v2, 24, v2
	v_and_b32_e32 v3, 4, v3
	v_bfe_u32 v4, v140, 2, 2
	v_lshlrev_b32_e32 v0, 4, v140
	v_and_b32_e32 v1, 32, v140
	v_bfe_u32 v10, v140, 2, 4
	v_or3_b32 v2, v3, v4, v2
	v_lshrrev_b32_e32 v3, 3, v140
	s_movk_i32 s1, 0x70
	v_bitop3_b32 v8, v0, v1, 48 bitop3:0x6c
	v_and_b32_e32 v9, 64, v140
	v_and_or_b32 v4, v3, s1, v10
	s_movk_i32 s1, 0x60
	v_add_u32_e32 v11, 0x2000, v0
	v_or_b32_e32 v1, v8, v9
	v_and_or_b32 v3, v3, s1, v2
	v_lshrrev_b32_e32 v0, 7, v11
	s_movk_i32 s1, 0xf0
	v_lshl_or_b32 v130, v3, 12, v1
	v_and_or_b32 v3, v0, s1, v10
	s_movk_i32 s1, 0xe0
	s_add_u32 s3, s74, 0xa1a2000
	v_and_or_b32 v0, v0, s1, v2
	s_mov_b32 s1, 0
	s_addc_u32 s10, s75, 0
	s_lshr_b32 s8, s12, 6
	s_mov_b32 s39, s1
	s_lshr_b32 s0, s12, 8
	s_lshl_b32 s11, s8, 10
	s_lshl_b64 s[4:5], s[38:39], 20
	s_add_u32 s44, s3, s4
	s_mov_b32 s43, s1
	s_addc_u32 s45, s10, s5
	s_lshl_b64 s[4:5], s[42:43], 20
	s_add_u32 s46, s74, s4
	s_addc_u32 s47, s75, s5
	s_add_i32 s14, s11, 0
	s_add_i32 m0, s14, 0x10000
	v_lshl_or_b32 v134, v0, 12, v1
	global_load_lds_dwordx4 v130, s[46:47]
	s_add_i32 m0, s14, 0x12000
	s_add_u32 s4, s46, 0x80000
	global_load_lds_dwordx4 v134, s[46:47]
	s_addc_u32 s5, s47, 0
	s_add_i32 m0, s14, 0x14000
	s_add_i32 s15, s14, 0x2000
	global_load_lds_dwordx4 v130, s[4:5]
	s_add_i32 m0, s14, 0x16000
	v_lshl_or_b32 v128, v4, 12, v1
	global_load_lds_dwordx4 v134, s[4:5]
	s_mov_b32 m0, s14
	s_add_u32 s4, s44, 0x80000
	v_lshl_or_b32 v132, v3, 12, v1
	global_load_lds_dwordx4 v128, s[44:45]
	s_mov_b32 m0, s15
	s_addc_u32 s5, s45, 0
	s_add_i32 s16, s14, 0x4000
	global_load_lds_dwordx4 v132, s[44:45]
	s_mov_b32 m0, s16
	s_add_i32 s17, s14, 0x6000
	global_load_lds_dwordx4 v128, s[4:5]
	s_mov_b32 m0, s17
	v_mov_b32_e32 v131, 0
	global_load_lds_dwordx4 v132, s[4:5]
	v_mov_b32_e32 v135, v131
	v_mov_b32_e32 v129, v131
	v_mov_b32_e32 v133, v131
	s_cmp_eq_u32 s0, 1
	v_lshl_add_u64 v[6:7], s[46:47], 0, v[130:131]
	v_lshl_add_u64 v[4:5], s[46:47], 0, v[134:135]
	v_lshl_add_u64 v[0:1], s[44:45], 0, v[128:129]
	s_cselect_b64 s[4:5], -1, 0
	s_cmp_lg_u32 s0, 1
	v_lshl_add_u64 v[2:3], s[44:45], 0, v[132:133]
	s_cbranch_scc1 .LBB0_161
	s_setprio 1
	s_barrier

;     __device__ bool next(int i, Unit& u) const {
;         long L = (long)i * G + c; u.ks = -1;
;         if (L < pre) { const int t = (int)L & 63; u.ks = (int)L >> 6; u.pm = nM + (t >> 3); u.pn = t & 7; return true; }
;         L -= pre;
;         if (L >= nwg + extra) return false;
;         if (L >= nwg) { const int j = (int)(L - nwg); const int q = j >> 3; u.pm = nM + (j & 7); u.pn = q < 6 ? q + 2 : 20; return true; }
;         int wgid = (int)L; { const int q = nwg / NXCD, r = nwg % NXCD, xcd = wgid % NXCD, off = wgid / NXCD; wgid = (xcd < r ? xcd * (q + 1) : r * (q + 1) + (xcd - r) * q) + off; }
;         const int wgm = nN <= 8 ? 4 : WGM;
;         const int nig = wgm * nN, gid = wgid / nig, fm = gid * wgm, gsz = (nM - fm) < wgm ? (nM - fm) : wgm;
;         u.pm = fm + ((wgid % nig) % gsz); u.pn = (wgid % nig) / gsz; return true;
.LBB0_230:
	s_setprio 0
	s_cmp_lt_i32 s76, 4
	s_cselect_b64 s[0:1], -1, 0
	s_cmp_gt_i32 s77, 3
	s_cselect_b64 s[4:5], -1, 0
	s_and_b64 s[0:1], s[0:1], s[4:5]
	s_andn2_b64 vcc, exec, s[0:1]
	s_cbranch_vccnz .LBB0_326
	s_ashr_i32 s3, s2, 31
	s_cmpk_gt_i32 s2, 0xff
	v_readfirstlane_b32 s24, v140
	s_cbranch_scc0 .LBB0_234
	s_add_u32 s6, s2, 0xffffff00
	s_addc_u32 s7, s3, -1
	v_mov_b64_e32 v[0:1], 0x3ff
	v_cmp_gt_u64_e32 vcc, s[6:7], v[0:1]
	s_mov_b64 s[4:5], 0
	s_mov_b64 s[0:1], 0
	s_cbranch_vccnz .LBB0_235
	s_lshr_b32 s0, s6, 3
	s_lshl_b32 s1, s6, 7
	s_or_b32 s0, s1, s0
	s_lshr_b32 s0, s0, 3
	s_and_b32 s0, s0, 0x7c
	s_bfe_u32 s1, s6, 0x20003
	s_or_b32 s0, s0, s1
	s_and_b32 s52, s0, 0x7f
	s_bfe_u32 s53, s6, 0x30005
	s_mov_b64 s[0:1], -1
	s_branch .LBB0_235

; #define PG8_STAGE(bufoff, gbase, voff) do { _Pragma("unroll") for (int _i = 0; _i < 2; ++_i) \
;         __builtin_amdgcn_global_load_lds((const unsigned*)((const char*)(gbase) + (voff)[_i]), (LAS unsigned*)(lds + (bufoff) + ldsw + _i * 8192), 16, 0, 0); } while (0)
; #define PG8_BAR __builtin_amdgcn_s_barrier()
; __device__ __forceinline__ void gemm_phase(LAS unsigned char* lds, const Params& p, const bf16_t* gA, const bf16_t* gBt, const int gM, const int gN, const int gK, const int epi, const int perm, bf16_t* const Hp, const int goff, const float coef) {
;     ...
;     for (int i = 0; i < 2; ++i) { int R, C; stage_rc(tid * 16 + i * 8192, R, C); const int Rb = perm ? ((R & ~31) + perm32(R & 31)) : R;
;         voffA[i] = (unsigned)(R * K + C) * 2u; voffB[i] = (unsigned)(Rb * K + C) * 2u; }
;     ...
;     const char* cA = (const char*)gA + (size_t)cur.pm * tstep + (cur.ks > 0 ? cur.ks * ksl : 0); const char* cB = (const char*)gBt + (size_t)cur.pn * tstep + (cur.ks > 0 ? cur.ks * ksl : 0);
;     PG8_STAGE(PG8_SB(0, 0), cB, voffB); PG8_STAGE(PG8_SB(0, 1), cB + hstep, voffB); PG8_STAGE(PG8_SA(0, 0), cA, voffA); PG8_STAGE(PG8_SA(0, 1), cA + hstep, voffA);
;     if (wr == 1) PG8_BAR;
.LBB0_243:
	s_add_u32 s10, s74, 0x129a4000
	s_addc_u32 s11, s75, 0
	s_mul_i32 s8, s52, 0x2c0000
	s_mul_hi_i32 s7, s52, 0x2c0000
	s_add_u32 s8, s10, s8
	s_addc_u32 s7, s11, s7
	s_add_u32 s14, s74, 0x2c00000
	s_addc_u32 s15, s75, 0
	s_add_u32 s30, s8, s4
	v_lshrrev_b32_e32 v3, 1, v140
	v_lshrrev_b32_e32 v4, 5, v140
	s_addc_u32 s31, s7, s5
	s_mul_i32 s5, s53, 0x2c0000
	v_and_b32_e32 v3, 24, v3
	v_and_b32_e32 v4, 4, v4
	v_bfe_u32 v5, v140, 2, 2
	s_mul_hi_i32 s4, s53, 0x2c0000
	s_add_u32 s7, s14, s5
	v_lshlrev_b32_e32 v0, 4, v140
	v_and_b32_e32 v1, 32, v140
	v_bfe_u32 v2, v140, 2, 4
	v_or3_b32 v3, v4, v5, v3
	v_lshrrev_b32_e32 v4, 3, v140
	s_movk_i32 s9, 0x70
	s_addc_u32 s8, s15, s4
	s_lshr_b32 s5, s24, 6
	v_bitop3_b32 v8, v0, v1, 48 bitop3:0x6c
	v_and_b32_e32 v9, 64, v140
	v_and_or_b32 v5, v4, s9, v2
	s_movk_i32 s9, 0x60
	v_add_u32_e32 v0, 0x2000, v0
	s_lshr_b32 s4, s24, 8
	v_or_b32_e32 v1, v8, v9
	v_and_or_b32 v4, v4, s9, v3
	v_lshrrev_b32_e32 v0, 7, v0
	s_movk_i32 s9, 0xf0
	s_lshl_b32 s16, s5, 10
	v_lshrrev_b32_e32 v1, 1, v1
	v_mul_u32_u24_e32 v4, 0x1600, v4
	v_and_or_b32 v2, v0, s9, v2
	s_movk_i32 s9, 0xe0
	s_add_u32 s34, s7, s0
	v_or_b32_e32 v4, v4, v1
	v_and_or_b32 v0, v0, s9, v3
	s_addc_u32 s35, s8, s1
	s_add_i32 s17, s16, 0
	v_lshlrev_b32_e32 v130, 1, v4
	v_mul_u32_u24_e32 v0, 0x1600, v0
	s_add_i32 m0, s17, 0x10000
	v_or_b32_e32 v0, v0, v1
	global_load_lds_dwordx4 v130, s[34:35]
	s_add_i32 m0, s17, 0x12000
	v_lshlrev_b32_e32 v134, 1, v0
	s_add_u32 s0, s34, 0x160000
	v_mul_u32_u24_e32 v10, 0x1600, v5
	global_load_lds_dwordx4 v134, s[34:35]
	s_addc_u32 s1, s35, 0
	s_add_i32 m0, s17, 0x14000
	v_or_b32_e32 v5, v1, v10
	v_mul_u32_u24_e32 v11, 0x1600, v2
	global_load_lds_dwordx4 v130, s[0:1]
	s_add_i32 m0, s17, 0x16000
	s_add_i32 s18, s17, 0x2000
	v_lshlrev_b32_e32 v128, 1, v5
	v_or_b32_e32 v2, v11, v1
	global_load_lds_dwordx4 v134, s[0:1]
	s_mov_b32 m0, s17
	s_add_u32 s0, s30, 0x160000
	v_lshlrev_b32_e32 v132, 1, v2
	global_load_lds_dwordx4 v128, s[30:31]
	s_mov_b32 m0, s18
	s_addc_u32 s1, s31, 0
	s_add_i32 s19, s17, 0x4000
	global_load_lds_dwordx4 v132, s[30:31]
	s_mov_b32 m0, s19
	s_add_i32 s20, s17, 0x6000
	global_load_lds_dwordx4 v128, s[0:1]
	s_mov_b32 m0, s20
	v_mov_b32_e32 v131, 0
	global_load_lds_dwordx4 v132, s[0:1]
	v_mov_b32_e32 v135, v131
	v_mov_b32_e32 v129, v131
	v_mov_b32_e32 v133, v131
	s_cmp_eq_u32 s4, 1
	s_mov_b32 s7, 0
	v_lshl_add_u64 v[6:7], s[34:35], 0, v[130:131]
	v_lshl_add_u64 v[4:5], s[34:35], 0, v[134:135]
	v_lshl_add_u64 v[0:1], s[30:31], 0, v[128:129]
	s_cselect_b64 s[8:9], -1, 0
	s_cmp_lg_u32 s4, 1
	v_lshl_add_u64 v[2:3], s[30:31], 0, v[132:133]
	s_cbranch_scc1 .LBB0_245
	s_setprio 1
	s_barrier

; __device__ __forceinline__ void norm_phase(const float* lat, const float* ctxp, const bf16_t* dbuf, const bf16_t* dbuf2, const bf16_t* dpart, float* xout, int nrows, const float* gw, const float* mod, int shift_off, int scale_off, bf16_t* outb, float* outf) {
;     const int wid = threadIdx.x >> 6, lane = threadIdx.x & 63;
;     const int nw = gridDim.x * 8, gwv = blockIdx.x * 8 + wid, per = (nrows + nw - 1) / nw;
;     const int rb = gwv * per, re = (rb + per < nrows) ? rb + per : nrows;
;     if (rb >= re) return;
;     int cur_b = -1;
;     f32x4 ca[8], cb[8], v[8]; u32x2 dv[8], dw[8];
;     { const float* src = rb < ML ? lat + (size_t)rb * D : ctxp + (size_t)(rb - ML) * D;
; #pragma unroll
;       for (int i = 0; i < 8; ++i) { v[i] = __builtin_nontemporal_load((const f32x4*)(src + i * 256 + lane * 4)); dv[i] = (u32x2){0u, 0u}; if (dbuf && !dpart) dv[i] = *(const u32x2*)(dbuf + (size_t)rb * D + i * 256 + lane * 4);
;           dw[i] = (u32x2){0u, 0u}; if (dbuf2) dw[i] = __builtin_nontemporal_load((const u32x2*)(dbuf2 + (size_t)rb * D + i * 256 + lane * 4)); } }
.LBB0_326:
	s_setprio 0
	s_cmp_lt_i32 s76, 5
	s_cselect_b64 s[0:1], -1, 0
	s_cmp_gt_i32 s77, 4
	s_cselect_b64 s[4:5], -1, 0
	s_and_b64 s[0:1], s[0:1], s[4:5]
	s_andn2_b64 vcc, exec, s[0:1]
	v_lshrrev_b32_e32 v244, 6, v140
	s_cbranch_vccnz .LBB0_408
	s_lshl_b32 s0, s78, 3
	s_abs_i32 s1, s0
	v_cvt_f32_u32_e32 v0, s1
	s_add_i32 s3, s0, 0x87ff
	s_sub_i32 s4, 0xffff7801, s0
	s_xor_b32 s0, s3, s0
	v_rcp_iflag_f32_e32 v0, v0
	s_max_i32 s3, s3, s4
	s_sub_i32 s4, 0, s1
	s_ashr_i32 s0, s0, 31
	v_mul_f32_e32 v0, 0x4f7ffffe, v0
	v_cvt_u32_f32_e32 v0, v0
	v_lshrrev_b32_e32 v1, 6, v140
	v_lshl_add_u32 v1, s2, 3, v1
	v_readfirstlane_b32 s5, v0
	s_mul_i32 s4, s4, s5
	s_mul_hi_u32 s4, s5, s4
	s_add_i32 s5, s5, s4
	s_mul_hi_u32 s4, s3, s5
	s_mul_i32 s5, s4, s1
	s_sub_i32 s3, s3, s5
	s_add_i32 s6, s4, 1
	s_sub_i32 s5, s3, s1
	s_cmp_ge_u32 s3, s1
	s_cselect_b32 s4, s6, s4
	s_cselect_b32 s3, s5, s3
	s_add_i32 s5, s4, 1
	s_cmp_ge_u32 s3, s1
	s_cselect_b32 s1, s5, s4
	s_xor_b32 s1, s1, s0
	s_sub_i32 s0, s1, s0
	v_mul_lo_u32 v128, s0, v1
	v_add_u32_e32 v0, s0, v128
	v_min_i32_e32 v135, 0x8800, v0
	v_cmp_lt_i32_e32 vcc, v128, v135
	s_and_saveexec_b64 s[6:7], vcc
	s_cbranch_execz .LBB0_354
	s_mov_b32 s3, 0x8000
	v_add_u32_e32 v0, 0xffff8000, v128
	v_ashrrev_i32_e32 v129, 31, v128
	v_cmp_gt_i32_e32 vcc, s3, v128
	v_mov_b32_e32 v2, s41
	v_mov_b32_e32 v3, s37
	v_cndmask_b32_e32 v1, 0, v129, vcc
	v_cndmask_b32_e32 v0, v0, v128, vcc
	v_cndmask_b32_e32 v3, v2, v3, vcc
	v_mov_b32_e32 v2, s40
	v_mov_b32_e32 v4, s36
	v_cndmask_b32_e32 v2, v2, v4, vcc
	v_lshlrev_b64 v[0:1], 13, v[0:1]
	v_lshl_add_u64 v[0:1], v[2:3], 0, v[0:1]
	v_lshlrev_b32_e32 v2, 2, v140
	v_and_b32_e32 v134, 0xfc, v2
	v_mov_b32_e32 v133, 0
	v_lshlrev_b32_e32 v132, 2, v134
	v_lshl_add_u64 v[0:1], v[0:1], 0, v[132:133]
	s_movk_i32 s14, 0x1000
	global_load_dwordx4 v[92:95], v[0:1], off nt
	global_load_dwordx4 v[88:91], v[0:1], off offset:1024 nt
	global_load_dwordx4 v[84:87], v[0:1], off offset:2048 nt
	global_load_dwordx4 v[72:75], v[0:1], off offset:3072 nt
	v_add_co_u32_e32 v0, vcc, s14, v0
	s_mov_b64 s[0:1], 0x2afa4000
	s_nop 0
	v_addc_co_u32_e32 v1, vcc, 0, v1, vcc
	global_load_dwordx4 v[80:83], v[0:1], off nt
	global_load_dwordx4 v[76:79], v[0:1], off offset:1024 nt
	global_load_dwordx4 v[68:71], v[0:1], off offset:2048 nt
	global_load_dwordx4 v[64:67], v[0:1], off offset:3072 nt
	v_lshlrev_b32_e32 v0, 1, v134
	v_mov_b32_e32 v1, v133
	v_lshl_add_u64 v[0:1], s[74:75], 0, v[0:1]
	v_readlane_b32 s44, v254, 2
	v_lshl_add_u64 v[136:137], v[0:1], 0, s[0:1]
	v_readlane_b32 s46, v254, 4
	v_readlane_b32 s47, v254, 5
	v_lshlrev_b64 v[14:15], 12, v[128:129]
	v_and_b32_e32 v1, 63, v140
	s_mov_b64 s[38:39], s[46:47]
	v_or_b32_e32 v6, 0x400, v134
	v_lshl_or_b32 v14, v1, 3, v14
	v_lshl_add_u64 v[138:139], s[38:39], 0, v[132:133]
	v_lshlrev_b32_e32 v132, 2, v6
	v_or_b32_e32 v8, 0x500, v134
	v_lshl_add_u64 v[14:15], s[74:75], 0, v[14:15]
	s_mov_b64 s[0:1], 0xa1a2000
	s_add_u32 s8, s74, 0xa100000
	v_lshl_add_u64 v[142:143], s[38:39], 0, v[132:133]
	v_lshlrev_b32_e32 v132, 2, v8
	v_or_b32_e32 v10, 0x600, v134
	v_lshl_add_u64 v[150:151], v[14:15], 0, s[0:1]
	v_lshlrev_b64 v[14:15], 13, v[128:129]
	s_addc_u32 s9, s75, 0
	v_or_b32_e32 v0, 0x100, v134
	v_lshl_add_u64 v[144:145], s[38:39], 0, v[132:133]
	v_lshlrev_b32_e32 v132, 2, v10
	v_or_b32_e32 v12, 0x700, v134
	v_lshl_or_b32 v14, v1, 4, v14
	s_cmp_lg_u64 s[72:73], 0
	v_or_b32_e32 v2, 0x200, v134
	v_or_b32_e32 v4, 0x300, v134
	v_lshl_add_u64 v[146:147], s[38:39], 0, v[132:133]
	v_lshlrev_b32_e32 v132, 2, v12
	v_lshl_add_u64 v[14:15], s[72:73], 0, v[14:15]
	s_mov_b64 s[10:11], 0x1000
	v_lshlrev_b32_e32 v154, 2, v0
	v_mbcnt_lo_u32_b32 v0, -1, 0
	s_mov_b64 s[12:13], 0
	s_cselect_b64 s[24:25], -1, 0
	v_lshl_add_u64 v[148:149], s[38:39], 0, v[132:133]
	v_lshl_add_u64 v[152:153], v[14:15], 0, s[10:11]
	v_mov_b32_e32 v155, -1
	s_mov_b64 s[26:27], 0x8000
	s_mov_b64 s[28:29], 0x6000
	v_lshlrev_b32_e32 v156, 2, v2
	v_lshlrev_b32_e32 v158, 2, v4
	v_lshlrev_b32_e32 v160, 2, v6
	v_lshlrev_b32_e32 v162, 2, v8
	v_lshlrev_b32_e32 v164, 2, v10
	v_lshlrev_b32_e32 v166, 2, v12
	s_movk_i32 s15, 0x7fff
	s_mov_b32 s16, 0x800000
	v_mov_b32_e32 v204, 0x358637bd
	s_mov_b64 s[30:31], 0x2000
	v_mbcnt_hi_u32_b32 v205, -1, v0
	v_readlane_b32 s45, v254, 3
	v_readlane_b32 s48, v254, 6
	v_readlane_b32 s49, v254, 7
	v_readlane_b32 s50, v254, 8
	v_readlane_b32 s51, v254, 9
	v_readlane_b32 s52, v254, 10
	v_readlane_b32 s53, v254, 11
	v_readlane_b32 s54, v254, 12
	v_readlane_b32 s55, v254, 13
	v_readlane_b32 s56, v254, 14
	v_readlane_b32 s57, v254, 15
	v_readlane_b32 s58, v254, 16
	v_readlane_b32 s59, v254, 17
	s_branch .LBB0_330

; #define PG8_STAGE(bufoff, gbase, voff) do { _Pragma("unroll") for (int _i = 0; _i < 2; ++_i) \
;         __builtin_amdgcn_global_load_lds((const unsigned*)((const char*)(gbase) + (voff)[_i]), (LAS unsigned*)(lds + (bufoff) + ldsw + _i * 8192), 16, 0, 0); } while (0)
; #define PG8_BAR __builtin_amdgcn_s_barrier()
; __device__ __forceinline__ void gemm_phase(LAS unsigned char* lds, const Params& p, const bf16_t* gA, const bf16_t* gBt, const int gM, const int gN, const int gK, const int epi, const int perm, bf16_t* const Hp, const int goff, const float coef) {
;     ...
;     for (int i = 0; i < 2; ++i) { int R, C; stage_rc(tid * 16 + i * 8192, R, C); const int Rb = perm ? ((R & ~31) + perm32(R & 31)) : R;
;         voffA[i] = (unsigned)(R * K + C) * 2u; voffB[i] = (unsigned)(Rb * K + C) * 2u; }
;     ...
;     const char* cA = (const char*)gA + (size_t)cur.pm * tstep + (cur.ks > 0 ? cur.ks * ksl : 0); const char* cB = (const char*)gBt + (size_t)cur.pn * tstep + (cur.ks > 0 ? cur.ks * ksl : 0);
;     PG8_STAGE(PG8_SB(0, 0), cB, voffB); PG8_STAGE(PG8_SB(0, 1), cB + hstep, voffB); PG8_STAGE(PG8_SA(0, 0), cA, voffA); PG8_STAGE(PG8_SA(0, 1), cA + hstep, voffA);
;     if (wr == 1) PG8_BAR;
.LBB0_421:
	v_lshrrev_b32_e32 v2, 1, v140
	v_lshrrev_b32_e32 v3, 5, v140
	v_and_b32_e32 v2, 24, v2
	v_and_b32_e32 v3, 4, v3
	v_bfe_u32 v4, v140, 2, 2
	s_add_u32 s3, s74, 0xa1a2000
	v_lshlrev_b32_e32 v0, 4, v140
	v_and_b32_e32 v1, 32, v140
	v_bfe_u32 v10, v140, 2, 4
	v_or3_b32 v2, v3, v4, v2
	v_lshrrev_b32_e32 v3, 3, v140
	s_movk_i32 s0, 0x70
	s_addc_u32 s27, s75, 0
	v_bitop3_b32 v8, v0, v1, 48 bitop3:0x6c
	v_and_b32_e32 v9, 64, v140
	v_and_or_b32 v4, v3, s0, v10
	s_movk_i32 s0, 0x60
	v_add_u32_e32 v11, 0x2000, v0
	s_add_u32 s29, s74, 0x4200000
	v_or_b32_e32 v1, v8, v9
	v_and_or_b32 v3, v3, s0, v2
	v_lshrrev_b32_e32 v0, 7, v11
	s_movk_i32 s0, 0xf0
	s_addc_u32 s31, s75, 0
	s_lshr_b32 s10, s6, 6
	v_lshl_or_b32 v144, v3, 12, v1
	v_and_or_b32 v3, v0, s0, v10
	s_movk_i32 s0, 0xe0
	s_ashr_i32 s45, s44, 31
	s_lshr_b32 s12, s6, 8
	v_and_or_b32 v0, v0, s0, v2
	s_lshl_b32 s52, s10, 10
	s_lshl_b64 s[0:1], s[44:45], 20
	s_add_u32 s0, s3, s0
	s_addc_u32 s1, s27, s1
	s_ashr_i32 s47, s46, 31
	s_lshl_b64 s[4:5], s[46:47], 20
	s_add_u32 s4, s29, s4
	s_addc_u32 s5, s31, s5
	s_add_i32 s47, s52, 0
	s_add_i32 m0, s47, 0x10000
	v_lshl_or_b32 v148, v0, 12, v1
	global_load_lds_dwordx4 v144, s[4:5]
	s_add_i32 m0, s47, 0x12000
	s_add_u32 s8, s4, 0x80000
	global_load_lds_dwordx4 v148, s[4:5]
	s_addc_u32 s9, s5, 0
	s_add_i32 m0, s47, 0x14000
	s_add_i32 s53, s47, 0x2000
	global_load_lds_dwordx4 v144, s[8:9]
	s_add_i32 m0, s47, 0x16000
	v_lshl_or_b32 v142, v4, 12, v1
	global_load_lds_dwordx4 v148, s[8:9]
	s_mov_b32 m0, s47
	s_add_u32 s8, s0, 0x80000
	v_lshl_or_b32 v146, v3, 12, v1
	global_load_lds_dwordx4 v142, s[0:1]
	s_mov_b32 m0, s53
	s_addc_u32 s9, s1, 0
	s_add_i32 s54, s47, 0x4000
	global_load_lds_dwordx4 v146, s[0:1]
	s_mov_b32 m0, s54
	s_add_i32 s55, s47, 0x6000
	global_load_lds_dwordx4 v142, s[8:9]
	s_mov_b32 m0, s55
	v_mov_b32_e32 v151, 0
	global_load_lds_dwordx4 v146, s[8:9]
	v_mov_b32_e32 v145, v151
	v_mov_b32_e32 v149, v151
	v_mov_b32_e32 v143, v151
	v_mov_b32_e32 v147, v151
	s_cmp_eq_u32 s12, 1
	s_mov_b32 s7, 0
	v_lshl_add_u64 v[6:7], s[4:5], 0, v[144:145]
	v_lshl_add_u64 v[4:5], s[4:5], 0, v[148:149]
	v_lshl_add_u64 v[0:1], s[0:1], 0, v[142:143]
	s_cselect_b64 s[8:9], -1, 0
	s_cmp_lg_u32 s12, 1
	v_lshl_add_u64 v[2:3], s[0:1], 0, v[146:147]
	s_cbranch_scc1 .LBB0_423
	s_setprio 1
	s_barrier

; #define LAS __attribute__((address_space(3)))
; __device__ __forceinline__ unsigned cvt_pk_bf16(float lo, float hi) { unsigned r; asm volatile("v_cvt_pk_bf16_f32 %0, %1, %2" : "=v"(r) : "v"(lo), "v"(hi)); return r; }
; __device__ __forceinline__ void gmlp_unit(const Params& p, LAS unsigned char* lds, int unit) {
;     LAS bf16_t* Wt = (LAS bf16_t*)lds;
;     LAS bf16_t* vnT = (LAS bf16_t*)(lds + 34816);
;     LAS float* rstd = (LAS float*)(lds + 69632);
;     const int t = threadIdx.x, wid = t >> 6, lane = t & 63, fr = lane & 15, fq = lane >> 4;
;     const int r0 = unit * 128;
;     const bf16_t* U = (const bf16_t*)(p.ws + WS_U); const bf16_t* GV = (const bf16_t*)(p.ws + WS_GV); bf16_t* CAT = (bf16_t*)(p.ws + WS_CAT);
;     for (int q = wid; q < 128; q += 8) {
;         float ss = 0.f;
; #pragma unroll
;         for (int i = 0; i < 2; ++i) { const u32x4 v = *(const u32x4*)(GV + (size_t)(r0 + q) * 1024 + i * 512 + lane * 8);
; #pragma unroll
;             for (int c = 0; c < 8; ++c) { const float f = bfel(v, c); ss += f * f; } }
;         ss = wave_sum(ss);
;         if (lane == 0) rstd[q] = rsqrtf(ss * (1.f / 1024.f) + 1e-6f);
;     }
;     __syncthreads();
;     for (int g = 0; g < 8; ++g) {
;         const float* ws_ = p.in[17] + (size_t)g * 128 * 128;
; #pragma unroll
;         for (int i = 0; i < 8; ++i) { const int idx = t + 512 * i, pr = idx >> 5, q4 = (idx & 31) * 4; const f32x4 v = *(const f32x4*)(ws_ + pr * 128 + q4);
;             u32x2 o; o.x = cvt_pk_bf16(v[0], v[1]); o.y = cvt_pk_bf16(v[2], v[3]); *(LAS u32x2*)(Wt + pr * 136 + q4) = o; }
;         const float* gn = p.in[16] + g * 128;
; #pragma unroll
;         for (int i = 0; i < 4; ++i) { const int d8 = (t & 15) * 8, q = (t >> 4) + 32 * i; const u32x4 v = *(const u32x4*)(GV + (size_t)(r0 + q) * 1024 + g * 128 + d8); const float rs = rstd[q];
; #pragma unroll
;             for (int c = 0; c < 8; ++c) { const float f = bfel(v, c) * rs * gn[d8 + c]; vnT[(d8 + c) * 136 + q] = (bf16_t)(cvt_pk_bf16(f, 0.f) & 0xffffu); } }
; template <int ph> __device__ __forceinline__ void run_phase(const Params& p, LAS unsigned char* lds) {
;     ...
;     else if (ph == 6) { for (int u = blockIdx.x; u < 256 + 2176; u += gridDim.x) { if (u < 256) gmlp_unit(p, lds, u); else conv_unit(p, u - 256); } }
.LBB0_1280:
	s_setprio 0
	s_cmp_lt_i32 s76, 7
	s_cselect_b64 s[0:1], -1, 0
	s_cmp_gt_i32 s77, 6
	s_cselect_b64 s[4:5], -1, 0
	s_and_b64 s[0:1], s[0:1], s[4:5]
	s_andn2_b64 vcc, exec, s[0:1]
	s_cbranch_vccnz .LBB0_1390
	s_cmpk_gt_i32 s2, 0x97f
	s_cbranch_scc1 .LBB0_1336
	v_lshlrev_b32_e32 v0, 3, v140
	v_and_b32_e32 v97, 0xf8, v0
	v_and_b32_e32 v5, 0x78, v0
	v_and_b32_e32 v0, 48, v140
	v_add_u32_e32 v8, 0, v0
	v_lshrrev_b32_e32 v0, 5, v140
	v_add_u32_e32 v10, 0x200, v140
	v_mul_u32_u24_e32 v9, 0x110, v0
	v_lshrrev_b32_e32 v0, 5, v10
	v_add_u32_e32 v12, 0x600, v140
	v_mul_u32_u24_e32 v11, 0x110, v0
	v_lshrrev_b32_e32 v0, 5, v12
	v_add_u32_e32 v14, 0xa00, v140
	v_mul_u32_u24_e32 v13, 0x110, v0
	v_lshrrev_b32_e32 v0, 5, v14
	v_add_u32_e32 v16, 0xe00, v140
	v_lshrrev_b32_e32 v1, 2, v140
	v_mov_b32_e32 v99, 0
	v_mul_u32_u24_e32 v15, 0x110, v0
	v_lshrrev_b32_e32 v0, 5, v16
	v_lshlrev_b32_e32 v98, 8, v97
	v_and_b32_e32 v96, 0xf8, v1
	v_mul_u32_u24_e32 v17, 0x110, v0
	v_lshl_add_u64 v[0:1], s[74:75], 0, v[98:99]
	s_mov_b64 s[4:5], 0x371a4000
	v_lshl_add_u64 v[100:101], v[0:1], 0, s[4:5]
	v_lshlrev_b32_e32 v0, 11, v140
	v_and_b32_e32 v2, 63, v140
	v_and_b32_e32 v98, 0x7800, v0
	v_lshrrev_b32_e32 v138, 6, v140
	v_and_b32_e32 v3, 15, v140
	v_lshl_add_u64 v[0:1], s[74:75], 0, v[98:99]
	s_mov_b64 s[4:5], 0x34fa4000
	v_lshlrev_b32_e32 v98, 4, v2
	v_readlane_b32 s36, v254, 18
	v_lshl_or_b32 v7, v138, 4, v3
	v_lshl_add_u64 v[102:103], v[0:1], 0, s[4:5]
	v_lshl_add_u64 v[0:1], s[74:75], 0, v[98:99]
	s_mov_b64 s[4:5], 0x231a4000
	v_lshlrev_b32_e32 v98, 2, v5
	v_readlane_b32 s37, v254, 19
	v_lshl_add_u64 v[104:105], v[0:1], 0, s[4:5]
	v_readlane_b32 s40, v254, 22
	v_readlane_b32 s41, v254, 23
	v_lshl_add_u64 v[106:107], s[36:37], 0, v[98:99]
	v_lshlrev_b32_e32 v98, 2, v7
	v_lshrrev_b32_e32 v0, 1, v140
	v_lshl_add_u64 v[108:109], s[40:41], 0, v[98:99]
	v_and_b32_e32 v98, 24, v0
	v_and_b32_e32 v0, 31, v140
	s_movk_i32 s3, 0x110
	v_lshlrev_b32_e32 v114, 4, v0
	v_lshlrev_b32_e32 v0, 4, v16
	v_mad_u32_u24 v139, v7, s3, v8
	s_add_i32 s3, 0, 0x11000
	v_readlane_b32 s38, v254, 20
	v_readlane_b32 s39, v254, 21
	v_lshl_add_u64 v[110:111], s[74:75], 0, v[98:99]
	v_and_b32_e32 v98, 0x1fe00, v0
	s_add_u32 s10, s74, 0x129a4000
	v_lshl_add_u64 v[116:117], s[38:39], 0, v[98:99]
	v_lshlrev_b32_e32 v98, 4, v3
	s_addc_u32 s11, s75, 0
	v_lshl_add_u64 v[0:1], s[74:75], 0, v[98:99]
	s_add_u32 s12, s74, 0x273c4000
	v_lshl_add_u64 v[118:119], v[0:1], 0, s[4:5]
	v_lshlrev_b32_e32 v0, 4, v140
	s_addc_u32 s13, s75, 0
	v_and_b32_e32 v98, 0x3e00, v0
	v_lshlrev_b32_e32 v0, 4, v10
	v_lshrrev_b32_e32 v6, 4, v140
	s_add_u32 s18, s74, 0x16da4000
	v_lshl_add_u64 v[128:129], s[38:39], 0, v[98:99]
	v_and_b32_e32 v98, 0x7e00, v0
	v_lshlrev_b32_e32 v0, 4, v12
	v_lshl_add_u32 v142, v6, 2, s3
	s_addc_u32 s19, s75, 0
	v_lshl_add_u32 v146, v138, 2, s3
	s_lshl_b32 s3, s2, 7
	v_lshl_add_u64 v[130:131], s[38:39], 0, v[98:99]
	v_and_b32_e32 v98, 0xfe00, v0
	v_lshlrev_b32_e32 v0, 4, v14
	v_add_u32_e32 v4, 0, v97
	v_lshl_add_u32 v18, v6, 1, 0
	v_mul_u32_u24_e32 v19, 0x110, v5
	v_mul_u32_u24_e32 v20, 0x110, v3
	v_readlane_b32 s42, v254, 24
	v_readlane_b32 s43, v254, 25
	v_readlane_b32 s44, v254, 26
	v_or_b32_e32 v120, s3, v6
	v_lshl_add_u64 v[132:133], s[38:39], 0, v[98:99]
	v_and_b32_e32 v98, 0xfe00, v0
	v_mbcnt_lo_u32_b32 v0, -1, 0
	v_cmp_eq_u32_e64 s[0:1], 0, v2
	v_add_u32_e32 v143, 0x80, v142
	v_add_u32_e32 v144, 0x100, v142
	v_add_u32_e32 v145, 0x180, v142
	s_lshl_b32 s14, s78, 7
	v_add_u32_e32 v112, s3, v7
	v_mov_b32_e32 v115, v99
	v_add_u32_e32 v122, 32, v120
	v_or_b32_e32 v124, 64, v120
	v_add_u32_e32 v126, 0x60, v120
	v_lshl_add_u64 v[134:135], s[38:39], 0, v[98:99]
	s_movk_i32 s15, 0x1000
	s_movk_i32 s16, 0x2000
	s_mov_b32 s17, 0xffff0000
	s_mov_b64 s[20:21], 0x1000
	s_mov_b64 s[24:25], 0x2000
	s_mov_b64 s[26:27], 0x3000
	s_mov_b64 s[28:29], 0x4000
	s_movk_i32 s22, 0x4000
	s_mov_b64 s[30:31], 0x32fa3c00
	v_mov_b32_e32 v147, 0x358637bd
	s_mov_b32 s23, 0x800000
	s_movk_i32 s33, 0x77
	v_add_u32_e32 v148, v4, v9
	v_add_u32_e32 v149, v4, v11
	v_add_u32_e32 v150, v4, v13
	s_mov_b32 s40, 0x8000
	v_add_u32_e32 v151, v4, v15
	s_mov_b32 s41, 0xc000
	v_add_u32_e32 v152, v4, v17
	v_add_u32_e32 v153, v18, v19
	v_add_u32_e32 v154, v8, v20
	s_mov_b32 s42, 0x1f1a4000
	s_mov_b32 s43, 0x2afa4000
	s_mov_b64 s[34:35], 0x10000
	v_mbcnt_hi_u32_b32 v155, -1, v0
	s_mov_b32 s44, s2
	v_readlane_b32 s45, v254, 27
	v_readlane_b32 s46, v254, 28
	v_readlane_b32 s47, v254, 29
	v_readlane_b32 s48, v254, 30
	v_readlane_b32 s49, v254, 31
	v_readlane_b32 s50, v254, 32
	v_readlane_b32 s51, v254, 33
	s_branch .LBB0_1284

; #define PG8_STAGE(bufoff, gbase, voff) do { _Pragma("unroll") for (int _i = 0; _i < 2; ++_i) \
;         __builtin_amdgcn_global_load_lds((const unsigned*)((const char*)(gbase) + (voff)[_i]), (LAS unsigned*)(lds + (bufoff) + ldsw + _i * 8192), 16, 0, 0); } while (0)
; #define PG8_BAR __builtin_amdgcn_s_barrier()
; __device__ __forceinline__ void gemm_phase(LAS unsigned char* lds, const Params& p, const bf16_t* gA, const bf16_t* gBt, const int gM, const int gN, const int gK, const int epi, const int perm, bf16_t* const Hp, const int goff, const float coef) {
;     ...
;     for (int i = 0; i < 2; ++i) { int R, C; stage_rc(tid * 16 + i * 8192, R, C); const int Rb = perm ? ((R & ~31) + perm32(R & 31)) : R;
;         voffA[i] = (unsigned)(R * K + C) * 2u; voffB[i] = (unsigned)(Rb * K + C) * 2u; }
;     ...
;     const char* cA = (const char*)gA + (size_t)cur.pm * tstep + (cur.ks > 0 ? cur.ks * ksl : 0); const char* cB = (const char*)gBt + (size_t)cur.pn * tstep + (cur.ks > 0 ? cur.ks * ksl : 0);
;     PG8_STAGE(PG8_SB(0, 0), cB, voffB); PG8_STAGE(PG8_SB(0, 1), cB + hstep, voffB); PG8_STAGE(PG8_SA(0, 0), cA, voffA); PG8_STAGE(PG8_SA(0, 1), cA + hstep, voffA);
;     if (wr == 1) PG8_BAR;
.LBB0_1582:
	s_waitcnt vmcnt(0)
	v_lshrrev_b32_e32 v2, 1, v140
	v_lshrrev_b32_e32 v3, 5, v140
	s_add_u32 s3, s74, 0x2afa4000
	v_and_b32_e32 v2, 24, v2
	v_and_b32_e32 v3, 4, v3
	v_bfe_u32 v4, v140, 2, 2
	s_addc_u32 s33, s75, 0
	v_lshlrev_b32_e32 v0, 4, v140
	v_and_b32_e32 v1, 32, v140
	v_bfe_u32 v10, v140, 2, 4
	v_or3_b32 v2, v3, v4, v2
	v_lshrrev_b32_e32 v3, 3, v140
	s_movk_i32 s6, 0x70
	s_add_u32 s34, s74, 0x5700000
	v_bitop3_b32 v8, v0, v1, 48 bitop3:0x6c
	v_and_b32_e32 v9, 64, v140
	v_and_or_b32 v4, v3, s6, v10
	s_movk_i32 s6, 0x60
	v_add_u32_e32 v11, 0x2000, v0
	s_addc_u32 s35, s75, 0
	v_or_b32_e32 v1, v8, v9
	v_and_or_b32 v3, v3, s6, v2
	v_lshrrev_b32_e32 v0, 7, v11
	s_movk_i32 s6, 0xf0
	s_and_b32 s51, s5, 7
	s_mov_b32 s5, 0
	s_lshr_b32 s1, s10, 6
	v_lshl_or_b32 v138, v3, 12, v1
	v_and_or_b32 v3, v0, s6, v10
	s_movk_i32 s6, 0xe0
	s_mov_b32 s25, s5
	s_lshr_b32 s0, s10, 8
	v_and_or_b32 v0, v0, s6, v2
	s_lshl_b32 s36, s1, 10
	s_lshl_b64 s[6:7], s[24:25], 20
	s_add_u32 s26, s3, s6
	s_addc_u32 s27, s33, s7
	s_lshl_b32 s6, s51, 20
	s_add_u32 s28, s34, s6
	s_addc_u32 s29, s35, 0
	s_add_i32 s37, s36, 0
	s_add_i32 m0, s37, 0x10000
	v_lshl_or_b32 v144, v0, 12, v1
	global_load_lds_dwordx4 v138, s[28:29]
	s_add_i32 m0, s37, 0x12000
	s_add_u32 s6, s28, 0x80000
	global_load_lds_dwordx4 v144, s[28:29]
	s_addc_u32 s7, s29, 0
	s_add_i32 m0, s37, 0x14000
	s_add_i32 s38, s37, 0x2000
	global_load_lds_dwordx4 v138, s[6:7]
	s_add_i32 m0, s37, 0x16000
	v_lshl_or_b32 v136, v4, 12, v1
	global_load_lds_dwordx4 v144, s[6:7]
	s_mov_b32 m0, s37
	s_add_u32 s6, s26, 0x80000
	v_lshl_or_b32 v142, v3, 12, v1
	global_load_lds_dwordx4 v136, s[26:27]
	s_mov_b32 m0, s38
	s_addc_u32 s7, s27, 0
	s_add_i32 s39, s37, 0x4000
	global_load_lds_dwordx4 v142, s[26:27]
	s_mov_b32 m0, s39
	s_add_i32 s40, s37, 0x6000
	global_load_lds_dwordx4 v136, s[6:7]
	s_mov_b32 m0, s40
	v_mov_b32_e32 v139, 0
	global_load_lds_dwordx4 v142, s[6:7]
	v_mov_b32_e32 v145, v139
	v_mov_b32_e32 v137, v139
	v_mov_b32_e32 v143, v139
	s_cmp_eq_u32 s0, 1
	v_lshl_add_u64 v[6:7], s[28:29], 0, v[138:139]
	v_lshl_add_u64 v[4:5], s[28:29], 0, v[144:145]
	v_lshl_add_u64 v[0:1], s[26:27], 0, v[136:137]
	s_cselect_b64 s[6:7], -1, 0
	s_cmp_lg_u32 s0, 1
	v_lshl_add_u64 v[2:3], s[26:27], 0, v[142:143]
	s_cbranch_scc1 .LBB0_1584
	s_setprio 1
	s_barrier

; __device__ __forceinline__ void norm_phase(const float* lat, const float* ctxp, const bf16_t* dbuf, const bf16_t* dbuf2, const bf16_t* dpart, float* xout, int nrows, const float* gw, const float* mod, int shift_off, int scale_off, bf16_t* outb, float* outf) {
;     const int wid = threadIdx.x >> 6, lane = threadIdx.x & 63;
;     const int nw = gridDim.x * 8, gwv = blockIdx.x * 8 + wid, per = (nrows + nw - 1) / nw;
;     const int rb = gwv * per, re = (rb + per < nrows) ? rb + per : nrows;
;     if (rb >= re) return;
;     int cur_b = -1;
;     f32x4 ca[8], cb[8], v[8]; u32x2 dv[8], dw[8];
;     { const float* src = rb < ML ? lat + (size_t)rb * D : ctxp + (size_t)(rb - ML) * D;
; #pragma unroll
;       for (int i = 0; i < 8; ++i) { v[i] = __builtin_nontemporal_load((const f32x4*)(src + i * 256 + lane * 4)); dv[i] = (u32x2){0u, 0u}; if (dbuf && !dpart) dv[i] = *(const u32x2*)(dbuf + (size_t)rb * D + i * 256 + lane * 4);
;           dw[i] = (u32x2){0u, 0u}; if (dbuf2) dw[i] = __builtin_nontemporal_load((const u32x2*)(dbuf2 + (size_t)rb * D + i * 256 + lane * 4)); } }
.LBB0_1655:
	s_setprio 0
	s_cmp_lt_i32 s76, 12
	s_cselect_b64 s[0:1], -1, 0
	s_cmp_gt_i32 s77, 11
	s_cselect_b64 s[4:5], -1, 0
	s_and_b64 s[0:1], s[0:1], s[4:5]
	s_andn2_b64 vcc, exec, s[0:1]
	s_cbranch_vccnz .LBB0_1717
	s_lshl_b32 s0, s78, 3
	s_abs_i32 s1, s0
	s_waitcnt vmcnt(0)
	v_cvt_f32_u32_e32 v0, s1
	s_add_i32 s3, s0, 0x7fff
	s_sub_i32 s4, 0xffff8001, s0
	s_xor_b32 s0, s3, s0
	v_rcp_iflag_f32_e32 v0, v0
	s_max_i32 s3, s3, s4
	s_sub_i32 s4, 0, s1
	s_ashr_i32 s0, s0, 31
	v_mul_f32_e32 v0, 0x4f7ffffe, v0
	v_cvt_u32_f32_e32 v0, v0
	v_lshl_add_u32 v1, s2, 3, v244
	v_readfirstlane_b32 s5, v0
	s_mul_i32 s4, s4, s5
	s_mul_hi_u32 s4, s5, s4
	s_add_i32 s5, s5, s4
	s_mul_hi_u32 s4, s3, s5
	s_mul_i32 s5, s4, s1
	s_sub_i32 s3, s3, s5
	s_add_i32 s6, s4, 1
	s_sub_i32 s5, s3, s1
	s_cmp_ge_u32 s3, s1
	s_cselect_b32 s4, s6, s4
	s_cselect_b32 s3, s5, s3
	s_add_i32 s5, s4, 1
	s_cmp_ge_u32 s3, s1
	s_cselect_b32 s1, s5, s4
	s_xor_b32 s1, s1, s0
	s_sub_i32 s0, s1, s0
	v_mul_lo_u32 v128, s0, v1
	v_add_u32_e32 v0, s0, v128
	v_min_i32_e32 v196, 0x8000, v0
	v_cmp_lt_i32_e32 vcc, v128, v196
	s_and_saveexec_b64 s[4:5], vcc
	s_cbranch_execz .LBB0_1663
	v_ashrrev_i32_e32 v129, 31, v128
	v_lshlrev_b32_e32 v4, 2, v140
	v_and_b32_e32 v28, 0xfc, v4
	v_mov_b32_e32 v130, 0
	v_lshlrev_b64 v[32:33], 12, v[128:129]
	v_lshl_add_u64 v[4:5], s[74:75], 0, v[32:33]
	v_lshlrev_b32_e32 v6, 1, v28
	v_mov_b32_e32 v7, v130
	v_lshl_add_u64 v[4:5], v[4:5], 0, v[6:7]
	s_mov_b64 s[0:1], 0x32fa4000
	v_lshlrev_b64 v[0:1], 13, v[128:129]
	v_lshl_add_u64 v[34:35], v[4:5], 0, s[0:1]
	s_mov_b32 s0, 0x32fa4000
	v_lshl_add_u64 v[2:3], s[72:73], 0, v[0:1]
	v_lshlrev_b32_e32 v30, 2, v28
	v_mov_b32_e32 v31, v130
	v_add_co_u32_e32 v36, vcc, s0, v4
	v_lshl_add_u64 v[2:3], v[2:3], 0, v[30:31]
	s_nop 0
	v_addc_co_u32_e32 v37, vcc, 0, v5, vcc
	s_movk_i32 s0, 0x1000
	global_load_dwordx4 v[60:63], v[2:3], off nt
	global_load_dwordx4 v[48:51], v[2:3], off offset:1024 nt
	global_load_dwordx4 v[24:27], v[2:3], off offset:2048 nt
	global_load_dwordx4 v[20:23], v[2:3], off offset:3072 nt
	v_add_co_u32_e32 v2, vcc, s0, v2
	v_readlane_b32 s8, v254, 18
	s_nop 0
	v_addc_co_u32_e32 v3, vcc, 0, v3, vcc
	global_load_dwordx2 v[176:177], v[34:35], off offset:512
	global_load_dwordx2 v[174:175], v[34:35], off offset:1024
	global_load_dwordx2 v[172:173], v[34:35], off offset:1536
	global_load_dwordx2 v[170:171], v[34:35], off offset:2048
	global_load_dwordx4 v[16:19], v[2:3], off nt
	global_load_dwordx4 v[12:15], v[2:3], off offset:1024 nt
	global_load_dwordx4 v[8:11], v[2:3], off offset:2048 nt
	global_load_dwordx4 v[4:7], v[2:3], off offset:3072 nt
	global_load_dwordx2 v[178:179], v[36:37], off
	global_load_dwordx2 v[168:169], v[34:35], off offset:2560
	global_load_dwordx2 v[166:167], v[34:35], off offset:3072
	global_load_dwordx2 v[164:165], v[34:35], off offset:3584
	v_mbcnt_lo_u32_b32 v3, -1, 0
	v_readlane_b32 s9, v254, 19
	v_readlane_b32 s16, v254, 26
	v_readlane_b32 s17, v254, 27
	v_mbcnt_hi_u32_b32 v3, -1, v3
	s_mov_b64 s[8:9], s[16:17]
	v_and_b32_e32 v29, 64, v3
	v_lshl_add_u64 v[132:133], s[8:9], 0, v[30:31]
	v_add_u32_e32 v29, 64, v29
	v_xor_b32_e32 v31, 32, v3
	v_cmp_lt_i32_e32 vcc, v31, v29
	v_or_b32_e32 v36, 0x400, v28
	v_lshlrev_b32_e32 v38, 2, v36
	v_cndmask_b32_e32 v31, v3, v31, vcc
	v_lshlrev_b32_e32 v129, 2, v31
	v_xor_b32_e32 v31, 16, v3
	v_cmp_lt_i32_e32 vcc, v31, v29
	v_mov_b32_e32 v39, v130
	v_lshl_add_u64 v[134:135], s[8:9], 0, v[38:39]
	v_cndmask_b32_e32 v31, v3, v31, vcc
	v_lshlrev_b32_e32 v197, 2, v31
	v_xor_b32_e32 v31, 8, v3
	v_cmp_lt_i32_e32 vcc, v31, v29
	v_or_b32_e32 v38, 0x500, v28
	v_lshlrev_b32_e32 v40, 2, v38
	v_cndmask_b32_e32 v31, v3, v31, vcc
	v_lshlrev_b32_e32 v198, 2, v31
	v_xor_b32_e32 v31, 4, v3
	v_cmp_lt_i32_e32 vcc, v31, v29
	v_mov_b32_e32 v41, v130
	v_lshl_add_u64 v[136:137], s[8:9], 0, v[40:41]
	v_cndmask_b32_e32 v31, v3, v31, vcc
	v_lshlrev_b32_e32 v199, 2, v31
	v_xor_b32_e32 v31, 2, v3
	v_cmp_lt_i32_e32 vcc, v31, v29
	v_or_b32_e32 v40, 0x600, v28
	v_lshlrev_b32_e32 v42, 2, v40
	v_cndmask_b32_e32 v31, v3, v31, vcc
	v_lshlrev_b32_e32 v200, 2, v31
	v_xor_b32_e32 v31, 1, v3
	v_cmp_lt_i32_e32 vcc, v31, v29
	v_mov_b32_e32 v43, v130
	v_lshl_add_u64 v[138:139], s[8:9], 0, v[42:43]
	v_cndmask_b32_e32 v3, v3, v31, vcc
	v_or_b32_e32 v42, 0x700, v28
	v_lshlrev_b32_e32 v201, 2, v3
	v_and_b32_e32 v3, 63, v140
	v_lshlrev_b32_e32 v44, 2, v42
	v_mov_b32_e32 v45, v130
	v_lshl_or_b32 v32, v3, 3, v32
	v_lshl_or_b32 v0, v3, 4, v0
	s_add_u32 s6, s74, 0xa100000
	v_readlane_b32 s10, v254, 20
	v_readlane_b32 s11, v254, 21
	v_readlane_b32 s12, v254, 22
	v_readlane_b32 s13, v254, 23
	v_readlane_b32 s14, v254, 24
	v_readlane_b32 s15, v254, 25
	v_readlane_b32 s18, v254, 28
	v_readlane_b32 s19, v254, 29
	v_or_b32_e32 v2, 0x100, v28
	v_or_b32_e32 v30, 0x200, v28
	v_or_b32_e32 v34, 0x300, v28
	v_lshl_add_u64 v[142:143], s[8:9], 0, v[44:45]
	v_lshl_add_u64 v[32:33], s[74:75], 0, v[32:33]
	s_mov_b64 s[0:1], 0x32fa5000
	v_lshl_add_u64 v[0:1], s[72:73], 0, v[0:1]
	s_mov_b64 s[8:9], 0x2000
	s_addc_u32 s7, s75, 0
	v_mov_b32_e32 v149, -1
	v_lshl_add_u64 v[144:145], v[32:33], 0, s[0:1]
	v_lshl_add_u64 v[146:147], v[0:1], 0, s[8:9]
	s_mov_b64 s[10:11], 0
	s_mov_b64 s[12:13], 0xe000
	s_mov_b64 s[14:15], 0xc000
	v_lshlrev_b32_e32 v148, 2, v28
	v_lshlrev_b32_e32 v150, 2, v2
	v_lshlrev_b32_e32 v152, 2, v30
	v_lshlrev_b32_e32 v154, 2, v34
	v_lshlrev_b32_e32 v156, 2, v36
	v_lshlrev_b32_e32 v158, 2, v38
	v_lshlrev_b32_e32 v160, 2, v40
	v_lshlrev_b32_e32 v162, 2, v42
	v_mov_b32_e32 v202, 0x358637bd
	s_mov_b32 s3, 0x800000
	s_mov_b32 s18, 0xd71fd000
	s_mov_b32 s19, 0xd71fe000
	s_mov_b64 s[16:17], 0x1000
	v_readlane_b32 s20, v254, 30
	v_readlane_b32 s21, v254, 31
	v_readlane_b32 s22, v254, 32
	v_readlane_b32 s23, v254, 33
	s_branch .LBB0_1659

; #define PG8_STAGE(bufoff, gbase, voff) do { _Pragma("unroll") for (int _i = 0; _i < 2; ++_i) \
;         __builtin_amdgcn_global_load_lds((const unsigned*)((const char*)(gbase) + (voff)[_i]), (LAS unsigned*)(lds + (bufoff) + ldsw + _i * 8192), 16, 0, 0); } while (0)
; #define PG8_BAR __builtin_amdgcn_s_barrier()
; __device__ __forceinline__ void gemm_phase(LAS unsigned char* lds, const Params& p, const bf16_t* gA, const bf16_t* gBt, const int gM, const int gN, const int gK, const int epi, const int perm, bf16_t* const Hp, const int goff, const float coef) {
;     ...
;     for (int i = 0; i < 2; ++i) { int R, C; stage_rc(tid * 16 + i * 8192, R, C); const int Rb = perm ? ((R & ~31) + perm32(R & 31)) : R;
;         voffA[i] = (unsigned)(R * K + C) * 2u; voffB[i] = (unsigned)(Rb * K + C) * 2u; }
;     ...
;     const char* cA = (const char*)gA + (size_t)cur.pm * tstep + (cur.ks > 0 ? cur.ks * ksl : 0); const char* cB = (const char*)gBt + (size_t)cur.pn * tstep + (cur.ks > 0 ? cur.ks * ksl : 0);
;     PG8_STAGE(PG8_SB(0, 0), cB, voffB); PG8_STAGE(PG8_SB(0, 1), cB + hstep, voffB); PG8_STAGE(PG8_SA(0, 0), cA, voffA); PG8_STAGE(PG8_SA(0, 1), cA + hstep, voffA);
;     if (wr == 1) PG8_BAR;
.LBB0_1726:
	s_waitcnt vmcnt(0)
	v_lshrrev_b32_e32 v2, 1, v140
	v_lshrrev_b32_e32 v3, 5, v140
	v_and_b32_e32 v2, 24, v2
	v_and_b32_e32 v3, 4, v3
	v_bfe_u32 v4, v140, 2, 2
	v_lshlrev_b32_e32 v0, 4, v140
	v_and_b32_e32 v1, 32, v140
	v_bfe_u32 v10, v140, 2, 4
	v_or3_b32 v2, v3, v4, v2
	v_lshrrev_b32_e32 v3, 3, v140
	s_movk_i32 s1, 0x70
	v_bitop3_b32 v8, v0, v1, 48 bitop3:0x6c
	v_and_b32_e32 v9, 64, v140
	v_and_or_b32 v4, v3, s1, v10
	s_movk_i32 s1, 0x60
	v_add_u32_e32 v11, 0x2000, v0
	s_add_u32 s3, s74, 0xa1a2000
	v_or_b32_e32 v1, v8, v9
	v_and_or_b32 v3, v3, s1, v2
	v_lshrrev_b32_e32 v0, 7, v11
	s_movk_i32 s1, 0xf0
	s_addc_u32 s33, s75, 0
	v_lshl_or_b32 v130, v3, 12, v1
	v_and_or_b32 v3, v0, s1, v10
	s_movk_i32 s1, 0xe0
	s_add_u32 s34, s74, 0x5f00000
	v_and_or_b32 v0, v0, s1, v2
	s_mov_b32 s1, 0
	s_addc_u32 s35, s75, 0
	s_lshr_b32 s8, s10, 6
	s_mov_b32 s23, s1
	s_lshr_b32 s0, s10, 8
	s_lshl_b32 s36, s8, 10
	s_lshl_b64 s[4:5], s[22:23], 20
	s_add_u32 s26, s3, s4
	s_mov_b32 s25, s1
	s_addc_u32 s27, s33, s5
	s_lshl_b64 s[4:5], s[24:25], 20
	s_add_u32 s28, s34, s4
	s_addc_u32 s29, s35, s5
	s_add_i32 s23, s36, 0
	s_add_i32 m0, s23, 0x10000
	v_lshl_or_b32 v134, v0, 12, v1
	global_load_lds_dwordx4 v130, s[28:29]
	s_add_i32 m0, s23, 0x12000
	s_add_u32 s4, s28, 0x80000
	global_load_lds_dwordx4 v134, s[28:29]
	s_addc_u32 s5, s29, 0
	s_add_i32 m0, s23, 0x14000
	s_add_i32 s25, s23, 0x2000
	global_load_lds_dwordx4 v130, s[4:5]
	s_add_i32 m0, s23, 0x16000
	v_lshl_or_b32 v128, v4, 12, v1
	global_load_lds_dwordx4 v134, s[4:5]
	s_mov_b32 m0, s23
	s_add_u32 s4, s26, 0x80000
	v_lshl_or_b32 v132, v3, 12, v1
	global_load_lds_dwordx4 v128, s[26:27]
	s_mov_b32 m0, s25
	s_addc_u32 s5, s27, 0
	s_add_i32 s37, s23, 0x4000
	global_load_lds_dwordx4 v132, s[26:27]
	s_mov_b32 m0, s37
	s_add_i32 s38, s23, 0x6000
	global_load_lds_dwordx4 v128, s[4:5]
	s_mov_b32 m0, s38
	v_mov_b32_e32 v131, 0
	global_load_lds_dwordx4 v132, s[4:5]
	v_mov_b32_e32 v135, v131
	v_mov_b32_e32 v129, v131
	v_mov_b32_e32 v133, v131
	s_cmp_eq_u32 s0, 1
	v_lshl_add_u64 v[6:7], s[28:29], 0, v[130:131]
	v_lshl_add_u64 v[4:5], s[28:29], 0, v[134:135]
	v_lshl_add_u64 v[0:1], s[26:27], 0, v[128:129]
	s_cselect_b64 s[4:5], -1, 0
	s_cmp_lg_u32 s0, 1
	v_lshl_add_u64 v[2:3], s[26:27], 0, v[132:133]
	s_cbranch_scc1 .LBB0_1728
	s_setprio 1
	s_barrier

;     __device__ bool next(int i, Unit& u) const {
;         long L = (long)i * G + c; u.ks = -1;
;         if (L < pre) { const int t = (int)L & 63; u.ks = (int)L >> 6; u.pm = nM + (t >> 3); u.pn = t & 7; return true; }
;         L -= pre;
;         if (L >= nwg + extra) return false;
;         if (L >= nwg) { const int j = (int)(L - nwg); const int q = j >> 3; u.pm = nM + (j & 7); u.pn = q < 6 ? q + 2 : 20; return true; }
;         int wgid = (int)L; { const int q = nwg / NXCD, r = nwg % NXCD, xcd = wgid % NXCD, off = wgid / NXCD; wgid = (xcd < r ? xcd * (q + 1) : r * (q + 1) + (xcd - r) * q) + off; }
;         const int wgm = nN <= 8 ? 4 : WGM;
;         const int nig = wgm * nN, gid = wgid / nig, fm = gid * wgm, gsz = (nM - fm) < wgm ? (nM - fm) : wgm;
;         u.pm = fm + ((wgid % nig) % gsz); u.pn = (wgid % nig) / gsz; return true;
.LBB0_1797:
	s_setprio 0
	s_cmp_lt_i32 s76, 14
	s_cselect_b64 s[0:1], -1, 0
	s_cmp_gt_i32 s77, 13
	s_cselect_b64 s[4:5], -1, 0
	s_and_b64 s[0:1], s[0:1], s[4:5]
	s_andn2_b64 vcc, exec, s[0:1]
	s_cbranch_vccnz .LBB0_1889
	v_readfirstlane_b32 s12, v140
	s_cmp_gt_i32 s2, -1
	s_mov_b32 s6, -1
	s_cbranch_scc0 .LBB0_1803
	s_mov_b64 s[4:5], 0
	s_cmpk_lt_u32 s2, 0x400
	s_mov_b64 s[0:1], 0
	s_cbranch_scc1 .LBB0_1804
	s_and_b64 vcc, exec, s[4:5]
	s_cbranch_vccnz .LBB0_1805

; #define PG8_STAGE(bufoff, gbase, voff) do { _Pragma("unroll") for (int _i = 0; _i < 2; ++_i) \
;         __builtin_amdgcn_global_load_lds((const unsigned*)((const char*)(gbase) + (voff)[_i]), (LAS unsigned*)(lds + (bufoff) + ldsw + _i * 8192), 16, 0, 0); } while (0)
; #define PG8_BAR __builtin_amdgcn_s_barrier()
; __device__ __forceinline__ void gemm_phase(LAS unsigned char* lds, const Params& p, const bf16_t* gA, const bf16_t* gBt, const int gM, const int gN, const int gK, const int epi, const int perm, bf16_t* const Hp, const int goff, const float coef) {
;     ...
;     for (int i = 0; i < 2; ++i) { int R, C; stage_rc(tid * 16 + i * 8192, R, C); const int Rb = perm ? ((R & ~31) + perm32(R & 31)) : R;
;         voffA[i] = (unsigned)(R * K + C) * 2u; voffB[i] = (unsigned)(Rb * K + C) * 2u; }
;     ...
;     const char* cA = (const char*)gA + (size_t)cur.pm * tstep + (cur.ks > 0 ? cur.ks * ksl : 0); const char* cB = (const char*)gBt + (size_t)cur.pn * tstep + (cur.ks > 0 ? cur.ks * ksl : 0);
;     PG8_STAGE(PG8_SB(0, 0), cB, voffB); PG8_STAGE(PG8_SB(0, 1), cB + hstep, voffB); PG8_STAGE(PG8_SA(0, 0), cA, voffA); PG8_STAGE(PG8_SA(0, 1), cA + hstep, voffA);
;     if (wr == 1) PG8_BAR;
.LBB0_1806:
	s_waitcnt vmcnt(0)
	v_lshrrev_b32_e32 v3, 1, v140
	v_lshrrev_b32_e32 v4, 5, v140
	v_and_b32_e32 v3, 24, v3
	v_and_b32_e32 v4, 4, v4
	v_bfe_u32 v5, v140, 2, 2
	v_lshlrev_b32_e32 v0, 4, v140
	v_and_b32_e32 v1, 32, v140
	v_bfe_u32 v2, v140, 2, 4
	v_or3_b32 v3, v4, v5, v3
	v_lshrrev_b32_e32 v4, 3, v140
	s_movk_i32 s4, 0x70
	s_add_u32 s3, s74, 0x129a4000
	v_bitop3_b32 v8, v0, v1, 48 bitop3:0x6c
	v_and_or_b32 v5, v4, s4, v2
	s_movk_i32 s4, 0x60
	v_add_u32_e32 v0, 0x2000, v0
	s_addc_u32 s24, s75, 0
	v_and_or_b32 v4, v4, s4, v3
	v_lshrrev_b32_e32 v0, 7, v0
	s_movk_i32 s4, 0xf0
	s_add_u32 s25, s74, 0x8b00000
	v_and_or_b32 v2, v0, s4, v2
	s_movk_i32 s4, 0xe0
	s_addc_u32 s26, s75, 0
	s_lshr_b32 s1, s12, 6
	v_and_or_b32 v0, v0, s4, v3
	s_mul_i32 s4, s48, 0x2c0000
	s_lshr_b32 s0, s12, 8
	s_lshl_b32 s27, s1, 10
	s_and_b32 s49, s7, 7
	s_ashr_i32 s5, s4, 31
	v_and_b32_e32 v9, 64, v140
	s_add_u32 s18, s3, s4
	v_or_b32_e32 v1, v8, v9
	s_addc_u32 s19, s24, s5
	s_mul_i32 s4, s49, 0x2c0000
	v_lshrrev_b32_e32 v1, 1, v1
	v_mul_u32_u24_e32 v4, 0x1600, v4
	s_add_u32 s20, s25, s4
	v_or_b32_e32 v4, v4, v1
	s_addc_u32 s21, s26, 0
	s_add_i32 s28, s27, 0
	v_lshlrev_b32_e32 v130, 1, v4
	v_mul_u32_u24_e32 v0, 0x1600, v0
	s_add_i32 m0, s28, 0x10000
	v_or_b32_e32 v0, v0, v1
	global_load_lds_dwordx4 v130, s[20:21]
	s_add_i32 m0, s28, 0x12000
	v_lshlrev_b32_e32 v134, 1, v0
	s_add_u32 s4, s20, 0x160000
	v_mul_u32_u24_e32 v10, 0x1600, v5
	global_load_lds_dwordx4 v134, s[20:21]
	s_addc_u32 s5, s21, 0
	s_add_i32 m0, s28, 0x14000
	v_or_b32_e32 v5, v1, v10
	v_mul_u32_u24_e32 v11, 0x1600, v2
	global_load_lds_dwordx4 v130, s[4:5]
	s_add_i32 m0, s28, 0x16000
	s_add_i32 s29, s28, 0x2000
	v_lshlrev_b32_e32 v128, 1, v5
	v_or_b32_e32 v2, v11, v1
	global_load_lds_dwordx4 v134, s[4:5]
	s_mov_b32 m0, s28
	s_add_u32 s4, s18, 0x160000
	v_lshlrev_b32_e32 v132, 1, v2
	global_load_lds_dwordx4 v128, s[18:19]
	s_mov_b32 m0, s29
	s_addc_u32 s5, s19, 0
	s_add_i32 s30, s28, 0x4000
	global_load_lds_dwordx4 v132, s[18:19]
	s_mov_b32 m0, s30
	s_add_i32 s31, s28, 0x6000
	global_load_lds_dwordx4 v128, s[4:5]
	s_mov_b32 m0, s31
	v_mov_b32_e32 v131, 0
	global_load_lds_dwordx4 v132, s[4:5]
	v_mov_b32_e32 v135, v131
	v_mov_b32_e32 v129, v131
	v_mov_b32_e32 v133, v131
	s_cmp_eq_u32 s0, 1
	s_mov_b32 s7, 0
	v_lshl_add_u64 v[6:7], s[20:21], 0, v[130:131]
	v_lshl_add_u64 v[4:5], s[20:21], 0, v[134:135]
	v_lshl_add_u64 v[0:1], s[18:19], 0, v[128:129]
	s_cselect_b64 s[8:9], -1, 0
	s_cmp_lg_u32 s0, 1
	v_lshl_add_u64 v[2:3], s[18:19], 0, v[132:133]
	s_cbranch_scc1 .LBB0_1808
	s_setprio 1
	s_barrier

; __device__ __forceinline__ void norm_phase(const float* lat, const float* ctxp, const bf16_t* dbuf, const bf16_t* dbuf2, const bf16_t* dpart, float* xout, int nrows, const float* gw, const float* mod, int shift_off, int scale_off, bf16_t* outb, float* outf) {
;     const int wid = threadIdx.x >> 6, lane = threadIdx.x & 63;
;     const int nw = gridDim.x * 8, gwv = blockIdx.x * 8 + wid, per = (nrows + nw - 1) / nw;
;     const int rb = gwv * per, re = (rb + per < nrows) ? rb + per : nrows;
;     if (rb >= re) return;
;     int cur_b = -1;
;     f32x4 ca[8], cb[8], v[8]; u32x2 dv[8], dw[8];
;     { const float* src = rb < ML ? lat + (size_t)rb * D : ctxp + (size_t)(rb - ML) * D;
; #pragma unroll
;       for (int i = 0; i < 8; ++i) { v[i] = __builtin_nontemporal_load((const f32x4*)(src + i * 256 + lane * 4)); dv[i] = (u32x2){0u, 0u}; if (dbuf && !dpart) dv[i] = *(const u32x2*)(dbuf + (size_t)rb * D + i * 256 + lane * 4);
;           dw[i] = (u32x2){0u, 0u}; if (dbuf2) dw[i] = __builtin_nontemporal_load((const u32x2*)(dbuf2 + (size_t)rb * D + i * 256 + lane * 4)); } }
.LBB0_1889:
	s_setprio 0
	s_cmp_lt_i32 s76, 15
	s_cselect_b64 s[0:1], -1, 0
	s_cmp_gt_i32 s77, 14
	s_cselect_b64 s[4:5], -1, 0
	s_and_b64 s[0:1], s[0:1], s[4:5]
	s_andn2_b64 vcc, exec, s[0:1]
	s_cbranch_vccnz .LBB0_1951
	s_lshl_b32 s0, s78, 3
	s_abs_i32 s1, s0
	s_waitcnt vmcnt(0)
	v_cvt_f32_u32_e32 v0, s1
	v_lshl_add_u32 v1, s2, 3, v244
	s_add_i32 s2, s0, 0x7fff
	s_sub_i32 s3, 0xffff8001, s0
	v_rcp_iflag_f32_e32 v0, v0
	s_xor_b32 s0, s2, s0
	s_max_i32 s2, s2, s3
	s_sub_i32 s3, 0, s1
	v_mul_f32_e32 v0, 0x4f7ffffe, v0
	v_cvt_u32_f32_e32 v0, v0
	s_ashr_i32 s0, s0, 31
	v_readfirstlane_b32 s4, v0
	s_mul_i32 s3, s3, s4
	s_mul_hi_u32 s3, s4, s3
	s_add_i32 s4, s4, s3
	s_mul_hi_u32 s3, s2, s4
	s_mul_i32 s4, s3, s1
	s_sub_i32 s2, s2, s4
	s_add_i32 s5, s3, 1
	s_sub_i32 s4, s2, s1
	s_cmp_ge_u32 s2, s1
	s_cselect_b32 s3, s5, s3
	s_cselect_b32 s2, s4, s2
	s_add_i32 s4, s3, 1
	s_cmp_ge_u32 s2, s1
	s_cselect_b32 s1, s4, s3
	s_xor_b32 s1, s1, s0
	s_sub_i32 s0, s1, s0
	v_mul_lo_u32 v96, s0, v1
	v_add_u32_e32 v0, s0, v96
	v_min_i32_e32 v178, 0x8000, v0
	v_cmp_lt_i32_e32 vcc, v96, v178
	s_and_saveexec_b64 s[2:3], vcc
	s_cbranch_execz .LBB0_1897
	v_ashrrev_i32_e32 v97, 31, v96
	v_lshlrev_b32_e32 v4, 2, v140
	v_and_b32_e32 v8, 0xfc, v4
	v_mov_b32_e32 v98, 0
	v_lshlrev_b64 v[6:7], 12, v[96:97]
	v_lshlrev_b32_e32 v4, 2, v8
	v_lshlrev_b32_e32 v8, 1, v8
	v_mov_b32_e32 v9, v98
	v_lshl_add_u64 v[10:11], s[74:75], 0, v[6:7]
	v_lshl_add_u64 v[8:9], v[10:11], 0, v[8:9]
	s_mov_b64 s[0:1], 0xa1a2000
	v_lshl_add_u64 v[10:11], v[8:9], 0, s[0:1]
	s_mov_b64 s[0:1], 0x32fa4000
	v_lshl_add_u64 v[12:13], v[8:9], 0, s[0:1]
	s_mov_b32 s0, 0xa1a2000
	v_add_co_u32_e32 v14, vcc, s0, v8
	v_lshlrev_b64 v[0:1], 13, v[96:97]
	s_nop 0
	v_addc_co_u32_e32 v15, vcc, 0, v9, vcc
	s_mov_b32 s0, 0x32fa4000
	v_lshl_add_u64 v[2:3], s[72:73], 0, v[0:1]
	v_mov_b32_e32 v5, v98
	v_add_co_u32_e32 v8, vcc, s0, v8
	v_lshl_add_u64 v[2:3], v[2:3], 0, v[4:5]
	s_nop 0
	v_addc_co_u32_e32 v9, vcc, 0, v9, vcc
	s_movk_i32 s10, 0x1000
	global_load_dwordx4 v[60:63], v[2:3], off nt
	global_load_dwordx4 v[56:59], v[2:3], off offset:1024 nt
	global_load_dwordx4 v[52:55], v[2:3], off offset:2048 nt
	global_load_dwordx4 v[48:51], v[2:3], off offset:3072 nt
	v_add_co_u32_e32 v2, vcc, s10, v2
	v_readlane_b32 s12, v254, 18
	s_nop 0
	v_addc_co_u32_e32 v3, vcc, 0, v3, vcc
	global_load_dwordx2 v[138:139], v[10:11], off offset:512
	global_load_dwordx2 v[134:135], v[10:11], off offset:1024
	global_load_dwordx2 v[130:131], v[10:11], off offset:1536
	global_load_dwordx2 v[126:127], v[10:11], off offset:2048
	global_load_dwordx4 v[44:47], v[2:3], off nt
	global_load_dwordx4 v[40:43], v[2:3], off offset:1024 nt
	global_load_dwordx2 v[136:137], v[12:13], off offset:1024 nt
	global_load_dwordx2 v[132:133], v[12:13], off offset:1536 nt
	global_load_dwordx2 v[128:129], v[12:13], off offset:2048 nt
	global_load_dwordx2 v[122:123], v[12:13], off offset:2560 nt
	global_load_dwordx4 v[36:39], v[2:3], off offset:2048 nt
	global_load_dwordx4 v[32:35], v[2:3], off offset:3072 nt
	global_load_dwordx2 v[142:143], v[12:13], off offset:512 nt
	global_load_dwordx2 v[124:125], v[10:11], off offset:2560
	global_load_dwordx2 v[118:119], v[10:11], off offset:3072
	global_load_dwordx2 v[114:115], v[10:11], off offset:3584
	global_load_dwordx2 v[144:145], v[14:15], off
	global_load_dwordx2 v[146:147], v[8:9], off nt
	global_load_dwordx2 v[120:121], v[12:13], off offset:3072 nt
	global_load_dwordx2 v[116:117], v[12:13], off offset:3584 nt
	v_readlane_b32 s14, v254, 20
	v_readlane_b32 s15, v254, 21
	v_readlane_b32 s26, v254, 32
	v_readlane_b32 s27, v254, 33
	s_mov_b64 s[14:15], s[26:27]
	v_or_b32_e32 v2, 0x1000, v4
	v_mov_b32_e32 v3, v98
	v_lshl_add_u64 v[102:103], s[14:15], 0, v[2:3]
	v_or_b32_e32 v2, 0x1400, v4
	v_lshl_add_u64 v[104:105], s[14:15], 0, v[2:3]
	v_or_b32_e32 v2, 0x1800, v4
	v_lshl_add_u64 v[106:107], s[14:15], 0, v[2:3]
	v_or_b32_e32 v2, 0x1c00, v4
	v_lshl_add_u64 v[108:109], s[14:15], 0, v[2:3]
	v_mbcnt_lo_u32_b32 v2, -1, 0
	v_mbcnt_hi_u32_b32 v2, -1, v2
	v_and_b32_e32 v3, 64, v2
	v_lshl_add_u64 v[100:101], s[14:15], 0, v[4:5]
	v_add_u32_e32 v3, 64, v3
	v_xor_b32_e32 v4, 32, v2
	v_cmp_lt_i32_e32 vcc, v4, v3
	s_mov_b64 s[0:1], 0x32fa5000
	v_mov_b32_e32 v181, -1
	v_cndmask_b32_e32 v4, v2, v4, vcc
	v_lshlrev_b32_e32 v97, 2, v4
	v_xor_b32_e32 v4, 16, v2
	v_cmp_lt_i32_e32 vcc, v4, v3
	s_mov_b64 s[4:5], 0
	v_mov_b32_e32 v185, 0x358637bd
	v_cndmask_b32_e32 v4, v2, v4, vcc
	v_lshlrev_b32_e32 v179, 2, v4
	v_xor_b32_e32 v4, 8, v2
	v_cmp_lt_i32_e32 vcc, v4, v3
	s_mov_b32 s11, 0x800000
	s_mov_b64 s[6:7], 0x2000
	v_cndmask_b32_e32 v4, v2, v4, vcc
	v_lshlrev_b32_e32 v180, 2, v4
	v_xor_b32_e32 v4, 4, v2
	v_cmp_lt_i32_e32 vcc, v4, v3
	s_mov_b64 s[8:9], 0x1000
	v_readlane_b32 s13, v254, 19
	v_cndmask_b32_e32 v4, v2, v4, vcc
	v_lshlrev_b32_e32 v182, 2, v4
	v_xor_b32_e32 v4, 2, v2
	v_cmp_lt_i32_e32 vcc, v4, v3
	v_readlane_b32 s16, v254, 22
	v_readlane_b32 s17, v254, 23
	v_cndmask_b32_e32 v4, v2, v4, vcc
	v_lshlrev_b32_e32 v183, 2, v4
	v_xor_b32_e32 v4, 1, v2
	v_cmp_lt_i32_e32 vcc, v4, v3
	v_readlane_b32 s18, v254, 24
	v_readlane_b32 s19, v254, 25
	v_cndmask_b32_e32 v2, v2, v4, vcc
	v_lshlrev_b32_e32 v184, 2, v2
	v_and_b32_e32 v2, 63, v140
	v_lshl_or_b32 v0, v2, 4, v0
	v_lshl_or_b32 v6, v2, 3, v6
	v_lshl_add_u64 v[110:111], s[72:73], 0, v[0:1]
	v_lshl_add_u64 v[0:1], s[74:75], 0, v[6:7]
	v_lshl_add_u64 v[112:113], v[0:1], 0, s[0:1]
	v_readlane_b32 s20, v254, 26
	v_readlane_b32 s21, v254, 27
	v_readlane_b32 s22, v254, 28
	v_readlane_b32 s23, v254, 29
	v_readlane_b32 s24, v254, 30
	v_readlane_b32 s25, v254, 31
	s_branch .LBB0_1893
